# P2 internal grid barrier split: arrive (L2 write-back + atomic) right after the dt/cumsum part, wait (one poll) after the conformer items
# baseline (speedup 1.0000x reference)
; __device__ __forceinline__ float bf2f(unsigned h) { return __uint_as_float(h << 16); }
; __global__ void __launch_bounds__(512, 2) mk_fwd(Args args) {
;     ...
;         {   const int gw = bx * 8 + wave, NGW = G * 8;
;             for (int it = gw; it < 64 * NH + (MS * NH) / 64; it += NGW) {
;                 if (it < 64 * NH) { const int ci = it >> 5, h = it & 31, rb = ci * 128;
;                     const float bias = dt_bias[h], A = -__expf(a_log[h]);
;                     const float v0 = bf2f(PROJ[(size_t)(rb + 2 * lane) * NPROJ + CDT + h]) + bias, v1 = bf2f(PROJ[(size_t)(rb + 2 * lane + 1) * NPROJ + CDT + h]) + bias;
;                     const float d0 = fmaxf(v0, 0.f) + log1pf(__expf(-fabsf(v0))), d1 = fmaxf(v1, 0.f) + log1pf(__expf(-fabsf(v1)));
;                     const float a1 = d1 * A; float sc = d0 * A + a1;
; #pragma unroll
;                     for (int o = 1; o < 64; o <<= 1) { const float t = __shfl_up(sc, o); if (lane >= o) sc += t; }
;                     DT[(size_t)(rb + 2 * lane) * NH + h] = d0; DT[(size_t)(rb + 2 * lane + 1) * NH + h] = d1;
;                     CS[(size_t)(rb + 2 * lane) * NH + h] = sc - a1; CS[(size_t)(rb + 2 * lane + 1) * NH + h] = sc; }
;                 else { const int e = (it - 64 * NH) * 64 + lane, row = MP + (e >> 5), h = e & 31;
;                     const float v = bf2f(PROJ[(size_t)row * NPROJ + CDT + h]) + dt_bias[h];
;                     DT[(size_t)row * NH + h] = fmaxf(v, 0.f) + log1pf(__expf(-fabsf(v))); }
;             }
;         }
;         if (psel != 1) {
;             cf_prompt_items(lds, PROJ, vbx, G, 1024, cf_conv_w, cf_conv_b, CONVOUT, out + O_PCFC);
.LBB0_215:
	s_waitcnt vmcnt(0)
	s_barrier
	v_readlane_b32 s8, v253, 4
	v_readlane_b32 s9, v253, 5
	s_mov_b64 s[10:11], exec
	s_and_b64 s[8:9], s[10:11], s[8:9]
	s_mov_b64 exec, s[8:9]
	s_cbranch_execz .Lp2a_skip
	v_readlane_b32 s8, v253, 12
	v_readlane_b32 s9, v253, 13
	buffer_wbl2 sc1
	s_waitcnt vmcnt(0)
	v_mov_b32_e32 v0, 0
	v_mov_b32_e32 v1, 1
	s_nop 2
	global_atomic_add v0, v1, s[8:9] offset:128
.Lp2a_skip:
	s_mov_b64 exec, s[10:11]
	v_readlane_b32 s0, v253, 6
	s_cmp_lg_u32 s0, 1
	s_cbranch_scc0 .LBB0_296
	s_add_u32 s3, s18, 0x9890000
	s_load_dwordx4 s[8:11], s[22:23], 0x70
	s_addc_u32 s72, s19, 0
	s_add_u32 s6, s18, 0x168d0000
	s_addc_u32 s7, s19, 0
	v_mov_b32_e32 v44, v212
	v_readlane_b32 s0, v253, 2
	s_cmpk_gt_i32 s0, 0x3ff
	v_readfirstlane_b32 s0, v44
	s_cbranch_scc1 .LBB0_293
	v_readlane_b32 s5, v253, 2
	s_lshl_b32 s75, s5, 3
	s_bfe_i32 s4, s5, 0x1001c
	s_and_b32 s1, s75, 0xffffffe0
	s_lshr_b32 s4, s4, 21
	s_add_i32 s4, s1, s4
	s_and_b32 s4, s4, 0xfffff800
	s_ashr_i32 s0, s0, 6
	s_sub_i32 s4, s1, s4
	s_lshl_b32 s33, s5, 9
	s_and_b32 s38, s33, 0x600
	s_not_b32 s39, s4
	s_sub_i32 s74, s0, 30
	s_cmp_lt_i32 s0, 62
	s_cselect_b64 s[4:5], -1, 0
	s_cmp_gt_i32 s74, s39
	v_lshlrev_b32_e32 v0, 3, v44
	s_cselect_b64 s[12:13], -1, 0
	v_and_b32_e32 v13, 0x1f8, v0
	s_and_b64 s[12:13], s[4:5], s[12:13]
	v_mov_b32_e32 v0, 0
	s_andn2_b64 vcc, exec, s[12:13]
	v_lshlrev_b32_e32 v46, 1, v13
	s_cbranch_vccnz .LBB0_219
	s_add_i32 s12, s74, s1
	s_mul_hi_i32 s13, s12, 0x4a00
	s_mulk_i32 s12, 0x4a00
	s_add_u32 s12, s3, s12
	s_addc_u32 s13, s72, s13
	s_lshl_b32 s14, s38, 1
	s_add_u32 s12, s12, s14
	s_addc_u32 s13, s13, 0
	v_mov_b32_e32 v47, v0
	v_lshl_add_u64 v[0:1], s[12:13], 0, v[46:47]
	v_add_co_u32_e32 v0, vcc, 0x2000, v0
	s_nop 1
	v_addc_co_u32_e32 v1, vcc, 0, v1, vcc
	global_load_dwordx4 v[0:3], v[0:1], off offset:2048
	s_branch .LBB0_220

; __device__ __forceinline__ unsigned xb_ld(unsigned* p)              { return __hip_atomic_load(p, __ATOMIC_RELAXED, __HIP_MEMORY_SCOPE_AGENT); }
; __device__ __forceinline__ unsigned xb_add(unsigned* p, unsigned v) { return __hip_atomic_fetch_add(p, v, __ATOMIC_RELAXED, __HIP_MEMORY_SCOPE_AGENT); }
; #define XB_SPIN(cond, bar) do { unsigned _sp = 0; while (cond) { __builtin_amdgcn_s_sleep(1); \
;     if ((++_sp & 255u) == 0u) { if (xb_ld(&(bar)[XB_TMO])) break; if (_sp > XB_SPIN_CAP) { atomicAdd(&(bar)[XB_TMO], 1u); break; } } } } while (0)
; __device__ __forceinline__ void xcd_barrier(const XcdBarrier& b) {
;     asm volatile("s_waitcnt vmcnt(0)" ::: "memory");
;     __syncthreads();
;     if (threadIdx.x == 0) {
;         unsigned* bar = b.bar;
;         __builtin_amdgcn_s_waitcnt(0);
;         unsigned nloc = b.st[0], nx = b.st[1];
;         if (nloc == 0u) { xcd_barrier_complete(bar, b.x, nloc, nx); b.st[0] = nloc; b.st[1] = nx; }
;         const unsigned old = xb_add(&bar[XB_XSUB(b.x)], 1u);
;         const unsigned gen = old / nloc;
;         if (old + 1u == (gen + 1u) * nloc) {
;             __builtin_amdgcn_fence(__ATOMIC_RELEASE, "agent");
;             asm volatile("s_waitcnt vmcnt(0)" ::: "memory");
;             const unsigned og = xb_add(&bar[XB_TOP], 1u);
;             const unsigned tg = og / nx;
;             if (og + 1u == (tg + 1u) * nx) xb_add(&bar[XB_TOPGEN], 1u);
;             else XB_SPIN(xb_ld(&bar[XB_TOPGEN]) == tg, bar);
;             __builtin_amdgcn_fence(__ATOMIC_ACQUIRE, "agent");
;             xb_add(&bar[XB_XGEN(b.x)], 1u);
;             asm volatile("s_waitcnt vmcnt(0)" ::: "memory");
;         } else {
;             XB_SPIN(xb_ld(&bar[XB_XGEN(b.x)]) == gen, bar);
;             __builtin_amdgcn_fence(__ATOMIC_ACQUIRE, "agent");
;             asm volatile("s_waitcnt vmcnt(0)" ::: "memory");
;         }
;     }
;     __syncthreads();
; }
.Lcfs_done:
.LBB0_296:
	s_waitcnt vmcnt(0)
	s_waitcnt vmcnt(0) lgkmcnt(0)
	s_barrier
	s_mov_b64 s[0:1], exec
	v_readlane_b32 s4, v253, 4
	v_readlane_b32 s5, v253, 5
	s_and_b64 s[4:5], s[0:1], s[4:5]
	s_mov_b64 exec, s[4:5]
	s_cbranch_execz .LBB0_348
	v_mov_b32_e32 v0, 0
	s_mov_b32 s4, 0
.Lp2w_spin:
	global_load_dword v1, v0, s[74:75] offset:128 sc1
	s_waitcnt vmcnt(0)
	v_readfirstlane_b32 s3, v1
	s_add_u32 s4, s4, 1
	s_cmp_ge_u32 s3, s94
	s_cbranch_scc1 .Lp2w_done
	s_cmp_lt_u32 s4, 0x4000
	s_cbranch_scc0 .Lp2w_done
	s_sleep 1
	s_branch .Lp2w_spin
.Lp2w_done:
	buffer_inv sc1
	s_waitcnt vmcnt(0)
